# FFN gate/up tile loops only: next-tile index computation moved into the first K-iteration load segment
# baseline (speedup 1.0000x reference)
; #define PG8_STAGE(bufoff, gbase, voff) do { _Pragma("unroll") for (int _i = 0; _i < 2; ++_i) \
;         __builtin_amdgcn_global_load_lds((const unsigned*)((const char*)(gbase) + (voff)[_i]), (PG8_LAS unsigned*)(lds + (bufoff) + ldsw + _i * 8192), 16, 0, 0); } while (0)
; #define PG8_LDA(dst, b, h) do { _Pragma("unroll") for (int m = 0; m < 4; ++m) _Pragma("unroll") for (int k = 0; k < 2; ++k) dst[m][k] = *(const PG8_LAS bf16x8*)(lds + PG8_SA(b, h) + aoff + m * 2048 + k * 1024); } while (0)
; #define PG8_LDB(dst, b, h) do { _Pragma("unroll") for (int n = 0; n < 2; ++n) _Pragma("unroll") for (int k = 0; k < 2; ++k) dst[n][k] = *(const PG8_LAS bf16x8*)(lds + PG8_SB(b, h) + boff + n * 2048 + k * 1024); } while (0)
;     __host__ __device__ bool next(int i, Unit& u) const {
;         const long L = (long)i * G + c; if (L >= nwg) return false;
;         int wgid = (int)L; { const int q = nwg / NXCD, r = nwg % NXCD, xcd = wgid % NXCD, off = wgid / NXCD; wgid = (xcd < r ? xcd * (q + 1) : r * (q + 1) + (xcd - r) * q) + off; }
;         const int nig = WGM * nN, gid = wgid / nig, fm = gid * WGM, gsz = (nM - fm) < WGM ? (nM - fm) : WGM;
;         u.pm = fm + ((wgid % nig) % gsz); u.pn = (wgid % nig) / gsz; return true;
; template <class Epi, class Sched, bool ALIGN_EPI = false, bool SP2 = false, bool TA = true>
; __device__ __forceinline__ void gemm_phase(PG8_LAS unsigned char* lds, const Gemm g, const Sched& S, const Epi& E) {
;     ...
;         const bool has_next = S.next(ui + 1, nxt);
;         const char* nA = has_next ? (const char*)g.A + (size_t)nxt.pm * tstep : cA; const char* nB = has_next ? (const char*)g.Bt + (size_t)nxt.pn * tstep : cB;
; #pragma unroll 1
;         for (int t = 0; t < nt; t += 2) {
;             const bool last = (t == nt - 2);
;             const char* a1 = cA + (size_t)(t + 1) * kstep;
;             const char* a2 = last ? nA : cA + (size_t)(t + 2) * kstep; const char* b2 = last ? nB : cB + (size_t)(t + 2) * kstepB;
;             const char* a3 = a2 + kstep; const char* b3 = b2 + kstepB;
;             if (last && has_next) S.a_ready(nxt);
;             if constexpr (SP2) {
;             PG8_LDB(B0, 0, 0); PG8_LDB(B1, 0, 1); PG8_SCHED; PG8_LDA(At, 0, 0); PG8_STAGE(PG8_SA(1, 1), a1 + hstep, voffA);
;             PG8_WAIT_V(8); PG8_WAIT_L(0); PG8_BAR; PG8_MMA(0, 0, At, B0); PG8_MMA(0, 1, At, B1); PG8_BAR; PG8_SCHED;
.LBB0_787:
	s_add_u32 s70, s70, 0x44000
	s_addc_u32 s71, s71, 0
	s_add_u32 s72, s72, 0x8000
	s_addc_u32 s73, s73, 0
	s_mov_b32 s80, -2
	ds_read_b128 v[136:139], v147
	ds_read_b128 v[152:155], v147 offset:1024
	ds_read_b128 v[156:159], v147 offset:2048
	ds_read_b128 v[160:163], v147 offset:3072
	ds_read_b128 v[164:167], v148
	ds_read_b128 v[168:171], v148 offset:1024
	ds_read_b128 v[172:175], v148 offset:2048
	ds_read_b128 v[176:179], v148 offset:3072
	s_add_u32 s81, s70, 0xfffc4000
	s_addc_u32 s82, s71, -1
	s_cmp_eq_u32 s80, 12
	s_cselect_b32 s83, s55, s82
	s_cselect_b32 s82, s69, s81
	s_cselect_b32 s85, s53, s73
	s_cselect_b32 s84, s79, s72
	v_lshl_add_u64 v[140:141], s[70:71], 0, v[128:129]
	s_add_i32 m0, s23, 0xc000
	ds_read_b128 v[180:183], v149
	ds_read_b128 v[184:187], v149 offset:1024
	ds_read_b128 v[188:191], v149 offset:2048
	ds_read_b128 v[192:195], v149 offset:3072
	ds_read_b128 v[196:199], v149 offset:4096
	ds_read_b128 v[200:203], v149 offset:5120
	ds_read_b128 v[204:207], v149 offset:6144
	ds_read_b128 v[210:213], v149 offset:7168
	global_load_lds_dwordx4 v[140:141], off
	v_lshl_add_u64 v[140:141], v[140:141], 0, s[6:7]
	s_add_i32 m0, s23, 0xe000
	s_nop 0
	global_load_lds_dwordx4 v[140:141], off
	s_add_i32 s78, s61, 1
	s_mul_i32 s4, s78, s43
	s_mul_hi_u32 s5, s78, s74
	s_add_i32 s5, s5, s4
	s_mul_i32 s4, s78, s74
	s_add_u32 s56, s4, s20
	s_addc_u32 s57, s5, s18
	v_cmp_gt_i64_e32 vcc, s[56:57], v[134:135]
	v_cmp_lt_i64_e64 s[4:5], s[56:57], v[132:133]
	s_cbranch_vccnz .LBB0_789
	s_ashr_i32 s52, s56, 31
	s_lshr_b32 s52, s52, 29
	s_add_i32 s52, s56, s52
	s_ashr_i32 s53, s52, 3
	s_and_b32 s52, s52, -8
	s_sub_i32 s52, s56, s52
	s_cmp_lt_i32 s52, 0
	s_cselect_b32 s54, s75, 0x160
	s_mul_i32 s52, s52, s54
	s_add_i32 s52, s52, s53
	s_mul_hi_i32 s53, s52, 0x2e8ba2e9
	s_lshr_b32 s54, s53, 31
	s_ashr_i32 s53, s53, 5
	s_add_i32 s53, s53, s54
	s_lshl_b32 s54, s53, 3
	s_sub_i32 s55, 0x80, s54
	s_min_i32 s55, s55, 8
	s_abs_i32 s56, s55
	v_cvt_f32_u32_e32 v0, s56
	s_sub_i32 s58, 0, s56
	s_mulk_i32 s53, 0xb0
	s_sub_i32 s53, s52, s53
	v_rcp_iflag_f32_e32 v0, v0
	s_abs_i32 s52, s53
	s_xor_b32 s57, s53, s55
	s_ashr_i32 s57, s57, 31
	v_mul_f32_e32 v0, 0x4f7ffffe, v0
	v_cvt_u32_f32_e32 v0, v0
	s_nop 0
	v_readfirstlane_b32 s59, v0
	s_mul_i32 s58, s58, s59
	s_mul_hi_u32 s58, s59, s58
	s_add_i32 s59, s59, s58
	s_mul_hi_u32 s58, s52, s59
	s_mul_i32 s59, s58, s56
	s_sub_i32 s52, s52, s59
	s_add_i32 s69, s58, 1
	s_sub_i32 s59, s52, s56
	s_cmp_ge_u32 s52, s56
	s_cselect_b32 s58, s69, s58
	s_cselect_b32 s52, s59, s52
	s_add_i32 s59, s58, 1
	s_cmp_ge_u32 s52, s56
	s_cselect_b32 s52, s59, s58
	s_xor_b32 s52, s52, s57
	s_sub_i32 s52, s52, s57
	s_mul_i32 s55, s52, s55
	s_sub_i32 s53, s53, s55
	s_add_i32 s54, s54, s53
.LBB0_789:
	s_ashr_i32 s55, s54, 31
	s_lshl_b64 s[56:57], s[54:55], 19
	s_add_u32 s56, s34, s56
	s_addc_u32 s57, s35, s57
	s_and_b64 s[58:59], s[4:5], exec
	s_cselect_b32 s55, s57, s71
	s_cselect_b32 s69, s56, s70
	s_ashr_i32 s53, s52, 31
	s_lshl_b64 s[58:59], s[52:53], 19
	s_add_u32 s58, s19, s58
	s_addc_u32 s59, s21, s59
	s_and_b64 s[98:99], s[4:5], exec
	s_cselect_b32 s53, s59, s73
	s_cselect_b32 s79, s58, s72
	s_waitcnt vmcnt(8)
	s_waitcnt lgkmcnt(0)
	s_barrier
	s_setprio 1
	s_waitcnt lgkmcnt(0)
	v_mfma_f32_16x16x32_bf16 v[124:127], v[136:139], v[180:183], 0
	v_mfma_f32_16x16x32_bf16 v[116:119], v[156:159], v[180:183], 0
	v_mfma_f32_16x16x32_bf16 v[108:111], v[136:139], v[188:191], 0
	v_mfma_f32_16x16x32_bf16 v[100:103], v[156:159], v[188:191], 0
	v_mfma_f32_16x16x32_bf16 v[92:95], v[136:139], v[196:199], 0
	v_mfma_f32_16x16x32_bf16 v[84:87], v[156:159], v[196:199], 0
	v_mfma_f32_16x16x32_bf16 v[76:79], v[136:139], v[204:207], 0
	v_mfma_f32_16x16x32_bf16 v[68:71], v[156:159], v[204:207], 0
	v_mfma_f32_16x16x32_bf16 v[124:127], v[152:155], v[184:187], v[124:127]
	v_mfma_f32_16x16x32_bf16 v[116:119], v[160:163], v[184:187], v[116:119]
	v_mfma_f32_16x16x32_bf16 v[108:111], v[152:155], v[192:195], v[108:111]
	v_mfma_f32_16x16x32_bf16 v[100:103], v[160:163], v[192:195], v[100:103]
	v_mfma_f32_16x16x32_bf16 v[92:95], v[152:155], v[200:203], v[92:95]
	v_mfma_f32_16x16x32_bf16 v[84:87], v[160:163], v[200:203], v[84:87]
	v_mfma_f32_16x16x32_bf16 v[76:79], v[152:155], v[210:213], v[76:79]
	v_mfma_f32_16x16x32_bf16 v[68:71], v[160:163], v[210:213], v[68:71]
	s_setprio 0
	s_setprio 1
	v_mfma_f32_16x16x32_bf16 v[120:123], v[164:167], v[180:183], 0
	v_mfma_f32_16x16x32_bf16 v[112:115], v[172:175], v[180:183], 0
	v_mfma_f32_16x16x32_bf16 v[104:107], v[164:167], v[188:191], 0
	v_mfma_f32_16x16x32_bf16 v[96:99], v[172:175], v[188:191], 0
	v_mfma_f32_16x16x32_bf16 v[88:91], v[164:167], v[196:199], 0
	v_mfma_f32_16x16x32_bf16 v[80:83], v[172:175], v[196:199], 0
	v_mfma_f32_16x16x32_bf16 v[72:75], v[164:167], v[204:207], 0
	v_mfma_f32_16x16x32_bf16 v[64:67], v[172:175], v[204:207], 0
	v_mfma_f32_16x16x32_bf16 v[120:123], v[168:171], v[184:187], v[120:123]
	v_mfma_f32_16x16x32_bf16 v[112:115], v[176:179], v[184:187], v[112:115]
	v_mfma_f32_16x16x32_bf16 v[104:107], v[168:171], v[192:195], v[104:107]
	v_mfma_f32_16x16x32_bf16 v[96:99], v[176:179], v[192:195], v[96:99]
	v_mfma_f32_16x16x32_bf16 v[88:91], v[168:171], v[200:203], v[88:91]
	v_mfma_f32_16x16x32_bf16 v[80:83], v[176:179], v[200:203], v[80:83]
	v_mfma_f32_16x16x32_bf16 v[72:75], v[168:171], v[210:213], v[72:75]
	v_mfma_f32_16x16x32_bf16 v[64:67], v[176:179], v[210:213], v[64:67]
	s_setprio 0
	s_barrier
; #define PG8_STAGE(bufoff, gbase, voff) do { _Pragma("unroll") for (int _i = 0; _i < 2; ++_i) \
;         __builtin_amdgcn_global_load_lds((const unsigned*)((const char*)(gbase) + (voff)[_i]), (PG8_LAS unsigned*)(lds + (bufoff) + ldsw + _i * 8192), 16, 0, 0); } while (0)
; #define PG8_LDA(dst, b, h) do { _Pragma("unroll") for (int m = 0; m < 4; ++m) _Pragma("unroll") for (int k = 0; k < 2; ++k) dst[m][k] = *(const PG8_LAS bf16x8*)(lds + PG8_SA(b, h) + aoff + m * 2048 + k * 1024); } while (0)
; #define PG8_LDB(dst, b, h) do { _Pragma("unroll") for (int n = 0; n < 2; ++n) _Pragma("unroll") for (int k = 0; k < 2; ++k) dst[n][k] = *(const PG8_LAS bf16x8*)(lds + PG8_SB(b, h) + boff + n * 2048 + k * 1024); } while (0)
; #define PG8_MMA(ai, bj, At, Bt) do { __builtin_amdgcn_s_setprio(1); _Pragma("unroll") for (int m = 0; m < 4; ++m) _Pragma("unroll") for (int n = 0; n < 2; ++n) _Pragma("unroll") for (int k = 0; k < 2; ++k) \
;         acc[ai][bj][m][n] = __builtin_amdgcn_mfma_f32_16x16x32_bf16(Bt[n][k], At[m][k], acc[ai][bj][m][n], 0, 0, 0); __builtin_amdgcn_s_setprio(0); } while (0)
; #define PG8_WAIT_V(n) asm volatile("s_waitcnt vmcnt(" #n ")" ::: "memory")
; #define PG8_WAIT_L(n) asm volatile("s_waitcnt lgkmcnt(" #n ")" ::: "memory")
; #define PG8_BAR __builtin_amdgcn_s_barrier()
; #define PG8_SCHED __builtin_amdgcn_sched_barrier(0)
; template <class Epi, class Sched, bool ALIGN_EPI = false, bool SP2 = false, bool TA = true>
; __device__ __forceinline__ void gemm_phase(PG8_LAS unsigned char* lds, const Gemm g, const Sched& S, const Epi& E) {
;     ...
;             PG8_LDA(At, 0, 1); PG8_STAGE(PG8_SB(0, 0), b2, voffB); PG8_STAGE(PG8_SB(0, 1), b2 + hstep, voffB); PG8_STAGE(PG8_SA(0, 0), a2, voffA);
;             PG8_WAIT_V(8); PG8_WAIT_L(0); PG8_BAR; PG8_MMA(1, 0, At, B0); PG8_MMA(1, 1, At, B1); PG8_BAR; PG8_SCHED;
;             PG8_LDB(B0, 1, 0); PG8_LDB(B1, 1, 1); PG8_SCHED; PG8_LDA(At, 1, 0); PG8_STAGE(PG8_SA(0, 1), a2 + hstep, voffA);
;             PG8_WAIT_V(8); PG8_WAIT_L(0); PG8_BAR; PG8_MMA(0, 0, At, B0); PG8_MMA(0, 1, At, B1); PG8_BAR; PG8_SCHED;
	s_add_i32 s81, s76, s22
	v_lshl_add_u64 v[140:141], s[84:85], 0, v[128:129]
	s_mov_b32 m0, s81
	ds_read_b128 v[180:183], v149 offset:16384
	ds_read_b128 v[184:187], v149 offset:17408
	ds_read_b128 v[188:191], v149 offset:18432
	ds_read_b128 v[192:195], v149 offset:19456
	ds_read_b128 v[196:199], v149 offset:20480
	ds_read_b128 v[200:203], v149 offset:21504
	ds_read_b128 v[204:207], v149 offset:22528
	ds_read_b128 v[210:213], v149 offset:23552
	global_load_lds_dwordx4 v[140:141], off
	v_lshl_add_u64 v[214:215], v[140:141], 0, s[6:7]
	s_add_i32 m0, s81, 0x2000
	s_add_i32 s81, s77, s22
	global_load_lds_dwordx4 v[214:215], off
	v_lshl_add_u64 v[214:215], v[140:141], 0, s[8:9]
	s_mov_b32 m0, s81
	s_nop 0
	global_load_lds_dwordx4 v[214:215], off
	v_lshl_add_u64 v[214:215], v[140:141], 0, s[10:11]
	s_add_i32 m0, s81, 0x2000
	s_nop 0
	global_load_lds_dwordx4 v[214:215], off
	v_lshl_add_u64 v[214:215], s[82:83], 0, v[128:129]
	s_mov_b32 m0, s23
	v_lshl_add_u64 v[216:217], v[214:215], 0, s[6:7]
	global_load_lds_dwordx4 v[214:215], off
	s_mov_b32 m0, s30
	s_nop 0
	global_load_lds_dwordx4 v[216:217], off
	s_waitcnt vmcnt(8)
	s_waitcnt lgkmcnt(0)
	s_barrier
	s_setprio 1
	s_waitcnt lgkmcnt(0)
	v_mfma_f32_16x16x32_bf16 v[60:63], v[136:139], v[180:183], 0
	v_mfma_f32_16x16x32_bf16 v[52:55], v[156:159], v[180:183], 0
	v_mfma_f32_16x16x32_bf16 v[44:47], v[136:139], v[188:191], 0
	v_mfma_f32_16x16x32_bf16 v[36:39], v[156:159], v[188:191], 0
	v_mfma_f32_16x16x32_bf16 v[28:31], v[136:139], v[196:199], 0
	v_mfma_f32_16x16x32_bf16 v[20:23], v[156:159], v[196:199], 0
	v_mfma_f32_16x16x32_bf16 v[12:15], v[136:139], v[204:207], 0
	v_mfma_f32_16x16x32_bf16 v[4:7], v[156:159], v[204:207], 0
	v_mfma_f32_16x16x32_bf16 v[60:63], v[152:155], v[184:187], v[60:63]
	v_mfma_f32_16x16x32_bf16 v[52:55], v[160:163], v[184:187], v[52:55]
	v_mfma_f32_16x16x32_bf16 v[44:47], v[152:155], v[192:195], v[44:47]
	v_mfma_f32_16x16x32_bf16 v[36:39], v[160:163], v[192:195], v[36:39]
	v_mfma_f32_16x16x32_bf16 v[28:31], v[152:155], v[200:203], v[28:31]
	v_mfma_f32_16x16x32_bf16 v[20:23], v[160:163], v[200:203], v[20:23]
	v_mfma_f32_16x16x32_bf16 v[12:15], v[152:155], v[210:213], v[12:15]
	v_mfma_f32_16x16x32_bf16 v[4:7], v[160:163], v[210:213], v[4:7]
	s_setprio 0
	s_setprio 1
	v_mfma_f32_16x16x32_bf16 v[56:59], v[164:167], v[180:183], 0
	v_mfma_f32_16x16x32_bf16 v[48:51], v[172:175], v[180:183], 0
	v_mfma_f32_16x16x32_bf16 v[40:43], v[164:167], v[188:191], 0
	v_mfma_f32_16x16x32_bf16 v[32:35], v[172:175], v[188:191], 0
	v_mfma_f32_16x16x32_bf16 v[24:27], v[164:167], v[196:199], 0
	v_mfma_f32_16x16x32_bf16 v[16:19], v[172:175], v[196:199], 0
	v_mfma_f32_16x16x32_bf16 v[8:11], v[164:167], v[204:207], 0
	v_mfma_f32_16x16x32_bf16 v[0:3], v[172:175], v[204:207], 0
	v_mfma_f32_16x16x32_bf16 v[56:59], v[168:171], v[184:187], v[56:59]
	v_mfma_f32_16x16x32_bf16 v[48:51], v[176:179], v[184:187], v[48:51]
	v_mfma_f32_16x16x32_bf16 v[40:43], v[168:171], v[192:195], v[40:43]
	v_mfma_f32_16x16x32_bf16 v[32:35], v[176:179], v[192:195], v[32:35]
	v_mfma_f32_16x16x32_bf16 v[24:27], v[168:171], v[200:203], v[24:27]
	v_mfma_f32_16x16x32_bf16 v[16:19], v[176:179], v[200:203], v[16:19]
	v_mfma_f32_16x16x32_bf16 v[8:11], v[168:171], v[210:213], v[8:11]
	v_mfma_f32_16x16x32_bf16 v[0:3], v[176:179], v[210:213], v[0:3]
	s_setprio 0
	s_barrier
	s_add_i32 s81, 0, 0x18000
	v_add_u32_e32 v130, s81, v144
	s_add_i32 s82, 0, 0x1c000
	ds_read_b128 v[136:139], v130
	ds_read_b128 v[152:155], v130 offset:1024
	ds_read_b128 v[156:159], v130 offset:2048
	ds_read_b128 v[160:163], v130 offset:3072
	v_add_u32_e32 v130, s82, v144
	ds_read_b128 v[164:167], v130
	ds_read_b128 v[168:171], v130 offset:1024
	ds_read_b128 v[172:175], v130 offset:2048
	ds_read_b128 v[176:179], v130 offset:3072
	s_mov_b32 m0, s31
	v_lshl_add_u64 v[216:217], v[214:215], 0, s[8:9]
	ds_read_b128 v[180:183], v149 offset:32768
	ds_read_b128 v[184:187], v149 offset:33792
	ds_read_b128 v[188:191], v149 offset:34816
	ds_read_b128 v[192:195], v149 offset:35840
	ds_read_b128 v[196:199], v149 offset:36864
	ds_read_b128 v[200:203], v149 offset:37888
	ds_read_b128 v[204:207], v149 offset:38912
	ds_read_b128 v[210:213], v149 offset:39936
	global_load_lds_dwordx4 v[216:217], off
	v_lshl_add_u64 v[216:217], v[214:215], 0, s[10:11]
	s_mov_b32 m0, s33
	s_nop 0
	global_load_lds_dwordx4 v[216:217], off
	s_waitcnt vmcnt(8)
	s_waitcnt lgkmcnt(0)
	s_barrier
; #define PG8_STAGE(bufoff, gbase, voff) do { _Pragma("unroll") for (int _i = 0; _i < 2; ++_i) \
;         __builtin_amdgcn_global_load_lds((const unsigned*)((const char*)(gbase) + (voff)[_i]), (PG8_LAS unsigned*)(lds + (bufoff) + ldsw + _i * 8192), 16, 0, 0); } while (0)
; #define PG8_LDA(dst, b, h) do { _Pragma("unroll") for (int m = 0; m < 4; ++m) _Pragma("unroll") for (int k = 0; k < 2; ++k) dst[m][k] = *(const PG8_LAS bf16x8*)(lds + PG8_SA(b, h) + aoff + m * 2048 + k * 1024); } while (0)
; #define PG8_MMA(ai, bj, At, Bt) do { __builtin_amdgcn_s_setprio(1); _Pragma("unroll") for (int m = 0; m < 4; ++m) _Pragma("unroll") for (int n = 0; n < 2; ++n) _Pragma("unroll") for (int k = 0; k < 2; ++k) \
;         acc[ai][bj][m][n] = __builtin_amdgcn_mfma_f32_16x16x32_bf16(Bt[n][k], At[m][k], acc[ai][bj][m][n], 0, 0, 0); __builtin_amdgcn_s_setprio(0); } while (0)
; #define PG8_WAIT_V(n) asm volatile("s_waitcnt vmcnt(" #n ")" ::: "memory")
; #define PG8_WAIT_L(n) asm volatile("s_waitcnt lgkmcnt(" #n ")" ::: "memory")
; #define PG8_BAR __builtin_amdgcn_s_barrier()
; #define PG8_SCHED __builtin_amdgcn_sched_barrier(0)
; template <class Epi, class Sched, bool ALIGN_EPI = false, bool SP2 = false, bool TA = true>
; __device__ __forceinline__ void gemm_phase(PG8_LAS unsigned char* lds, const Gemm g, const Sched& S, const Epi& E) {
;     ...
;         for (int t = 0; t < nt; t += 2) {
;     ...
;             PG8_WAIT_V(8); PG8_WAIT_L(0); PG8_BAR; PG8_MMA(0, 0, At, B0); PG8_MMA(0, 1, At, B1); PG8_BAR; PG8_SCHED;
;             PG8_LDA(At, 1, 1); PG8_STAGE(PG8_SB(1, 0), b3, voffB); PG8_STAGE(PG8_SB(1, 1), b3 + hstep, voffB); PG8_STAGE(PG8_SA(1, 0), a3, voffA);
;             PG8_WAIT_V(8); PG8_WAIT_L(0); PG8_BAR; PG8_MMA(1, 0, At, B0); PG8_MMA(1, 1, At, B1); PG8_BAR; PG8_SCHED;
	s_setprio 1
	s_waitcnt lgkmcnt(0)
	v_mfma_f32_16x16x32_bf16 v[124:127], v[136:139], v[180:183], v[124:127]
	v_mfma_f32_16x16x32_bf16 v[116:119], v[156:159], v[180:183], v[116:119]
	v_mfma_f32_16x16x32_bf16 v[108:111], v[136:139], v[188:191], v[108:111]
	v_mfma_f32_16x16x32_bf16 v[100:103], v[156:159], v[188:191], v[100:103]
	v_mfma_f32_16x16x32_bf16 v[92:95], v[136:139], v[196:199], v[92:95]
	v_mfma_f32_16x16x32_bf16 v[84:87], v[156:159], v[196:199], v[84:87]
	v_mfma_f32_16x16x32_bf16 v[76:79], v[136:139], v[204:207], v[76:79]
	v_mfma_f32_16x16x32_bf16 v[68:71], v[156:159], v[204:207], v[68:71]
	v_mfma_f32_16x16x32_bf16 v[124:127], v[152:155], v[184:187], v[124:127]
	v_mfma_f32_16x16x32_bf16 v[116:119], v[160:163], v[184:187], v[116:119]
	v_mfma_f32_16x16x32_bf16 v[108:111], v[152:155], v[192:195], v[108:111]
	v_mfma_f32_16x16x32_bf16 v[100:103], v[160:163], v[192:195], v[100:103]
	v_mfma_f32_16x16x32_bf16 v[92:95], v[152:155], v[200:203], v[92:95]
	v_mfma_f32_16x16x32_bf16 v[84:87], v[160:163], v[200:203], v[84:87]
	v_mfma_f32_16x16x32_bf16 v[76:79], v[152:155], v[210:213], v[76:79]
	v_mfma_f32_16x16x32_bf16 v[68:71], v[160:163], v[210:213], v[68:71]
	s_setprio 0
	s_setprio 1
	v_mfma_f32_16x16x32_bf16 v[120:123], v[164:167], v[180:183], v[120:123]
	v_mfma_f32_16x16x32_bf16 v[112:115], v[172:175], v[180:183], v[112:115]
	v_mfma_f32_16x16x32_bf16 v[104:107], v[164:167], v[188:191], v[104:107]
	v_mfma_f32_16x16x32_bf16 v[96:99], v[172:175], v[188:191], v[96:99]
	v_mfma_f32_16x16x32_bf16 v[88:91], v[164:167], v[196:199], v[88:91]
	v_mfma_f32_16x16x32_bf16 v[80:83], v[172:175], v[196:199], v[80:83]
	v_mfma_f32_16x16x32_bf16 v[72:75], v[164:167], v[204:207], v[72:75]
	v_mfma_f32_16x16x32_bf16 v[64:67], v[172:175], v[204:207], v[64:67]
	v_mfma_f32_16x16x32_bf16 v[120:123], v[168:171], v[184:187], v[120:123]
	v_mfma_f32_16x16x32_bf16 v[112:115], v[176:179], v[184:187], v[112:115]
	v_mfma_f32_16x16x32_bf16 v[104:107], v[168:171], v[192:195], v[104:107]
	v_mfma_f32_16x16x32_bf16 v[96:99], v[176:179], v[192:195], v[96:99]
	v_mfma_f32_16x16x32_bf16 v[88:91], v[168:171], v[200:203], v[88:91]
	v_mfma_f32_16x16x32_bf16 v[80:83], v[176:179], v[200:203], v[80:83]
	v_mfma_f32_16x16x32_bf16 v[72:75], v[168:171], v[210:213], v[72:75]
	v_mfma_f32_16x16x32_bf16 v[64:67], v[176:179], v[210:213], v[64:67]
	s_setprio 0
	s_barrier
	s_add_i32 s81, s81, s22
	v_lshl_add_u64 v[216:217], v[140:141], 0, s[16:17]
	s_mov_b32 m0, s81
	ds_read_b128 v[180:183], v149 offset:49152
	ds_read_b128 v[184:187], v149 offset:50176
	ds_read_b128 v[188:191], v149 offset:51200
	ds_read_b128 v[192:195], v149 offset:52224
	ds_read_b128 v[196:199], v149 offset:53248
	ds_read_b128 v[200:203], v149 offset:54272
	ds_read_b128 v[204:207], v149 offset:55296
	ds_read_b128 v[210:213], v149 offset:56320
	global_load_lds_dwordx4 v[216:217], off
	v_lshl_add_u64 v[216:217], v[140:141], 0, s[44:45]
	s_add_i32 m0, s81, 0x2000
	s_add_i32 s81, s82, s22
	global_load_lds_dwordx4 v[216:217], off
	v_lshl_add_u64 v[216:217], v[140:141], 0, s[46:47]
	s_mov_b32 m0, s81
	v_lshl_add_u64 v[140:141], v[140:141], 0, s[48:49]
	global_load_lds_dwordx4 v[216:217], off
	s_add_i32 m0, s81, 0x2000
	s_nop 0
	global_load_lds_dwordx4 v[140:141], off
	v_lshl_add_u64 v[140:141], v[214:215], 0, s[16:17]
	s_mov_b32 m0, s36
	s_nop 0
	global_load_lds_dwordx4 v[140:141], off
	v_lshl_add_u64 v[140:141], v[214:215], 0, s[44:45]
	s_mov_b32 m0, s37
	s_nop 0
	global_load_lds_dwordx4 v[140:141], off
	s_waitcnt vmcnt(8)
	s_waitcnt lgkmcnt(0)
	s_barrier
	s_setprio 1
	s_waitcnt lgkmcnt(0)
	v_mfma_f32_16x16x32_bf16 v[60:63], v[136:139], v[180:183], v[60:63]
	v_mfma_f32_16x16x32_bf16 v[52:55], v[156:159], v[180:183], v[52:55]
	v_mfma_f32_16x16x32_bf16 v[44:47], v[136:139], v[188:191], v[44:47]
	v_mfma_f32_16x16x32_bf16 v[36:39], v[156:159], v[188:191], v[36:39]
	v_mfma_f32_16x16x32_bf16 v[28:31], v[136:139], v[196:199], v[28:31]
	v_mfma_f32_16x16x32_bf16 v[20:23], v[156:159], v[196:199], v[20:23]
	v_mfma_f32_16x16x32_bf16 v[12:15], v[136:139], v[204:207], v[12:15]
	v_mfma_f32_16x16x32_bf16 v[4:7], v[156:159], v[204:207], v[4:7]
	v_mfma_f32_16x16x32_bf16 v[60:63], v[152:155], v[184:187], v[60:63]
	v_mfma_f32_16x16x32_bf16 v[52:55], v[160:163], v[184:187], v[52:55]
	v_mfma_f32_16x16x32_bf16 v[44:47], v[152:155], v[192:195], v[44:47]
	v_mfma_f32_16x16x32_bf16 v[36:39], v[160:163], v[192:195], v[36:39]
	v_mfma_f32_16x16x32_bf16 v[28:31], v[152:155], v[200:203], v[28:31]
	v_mfma_f32_16x16x32_bf16 v[20:23], v[160:163], v[200:203], v[20:23]
	v_mfma_f32_16x16x32_bf16 v[12:15], v[152:155], v[210:213], v[12:15]
	v_mfma_f32_16x16x32_bf16 v[4:7], v[160:163], v[210:213], v[4:7]
	s_setprio 0
	s_setprio 1
	v_mfma_f32_16x16x32_bf16 v[56:59], v[164:167], v[180:183], v[56:59]
	v_mfma_f32_16x16x32_bf16 v[48:51], v[172:175], v[180:183], v[48:51]
	v_mfma_f32_16x16x32_bf16 v[40:43], v[164:167], v[188:191], v[40:43]
	v_mfma_f32_16x16x32_bf16 v[32:35], v[172:175], v[188:191], v[32:35]
	v_mfma_f32_16x16x32_bf16 v[24:27], v[164:167], v[196:199], v[24:27]
	v_mfma_f32_16x16x32_bf16 v[16:19], v[172:175], v[196:199], v[16:19]
	v_mfma_f32_16x16x32_bf16 v[8:11], v[164:167], v[204:207], v[8:11]
	v_mfma_f32_16x16x32_bf16 v[0:3], v[172:175], v[204:207], v[0:3]
	v_mfma_f32_16x16x32_bf16 v[56:59], v[168:171], v[184:187], v[56:59]
	v_mfma_f32_16x16x32_bf16 v[48:51], v[176:179], v[184:187], v[48:51]
	v_mfma_f32_16x16x32_bf16 v[40:43], v[168:171], v[192:195], v[40:43]
	v_mfma_f32_16x16x32_bf16 v[32:35], v[176:179], v[192:195], v[32:35]
	v_mfma_f32_16x16x32_bf16 v[24:27], v[168:171], v[200:203], v[24:27]
	v_mfma_f32_16x16x32_bf16 v[16:19], v[176:179], v[200:203], v[16:19]
	v_mfma_f32_16x16x32_bf16 v[8:11], v[168:171], v[210:213], v[8:11]
	v_mfma_f32_16x16x32_bf16 v[0:3], v[176:179], v[210:213], v[0:3]
	s_setprio 0
	s_barrier
	s_add_i32 s80, s80, 2
	s_add_u32 s70, s70, 0x8000
	s_addc_u32 s71, s71, 0
	s_add_u32 s72, s72, 0x8000
	s_addc_u32 s73, s73, 0
	s_cmp_gt_u32 s80, 13

; #define PG8_STAGE(bufoff, gbase, voff) do { _Pragma("unroll") for (int _i = 0; _i < 2; ++_i) \
;         __builtin_amdgcn_global_load_lds((const unsigned*)((const char*)(gbase) + (voff)[_i]), (PG8_LAS unsigned*)(lds + (bufoff) + ldsw + _i * 8192), 16, 0, 0); } while (0)
; #define PG8_LDA(dst, b, h) do { _Pragma("unroll") for (int m = 0; m < 4; ++m) _Pragma("unroll") for (int k = 0; k < 2; ++k) dst[m][k] = *(const PG8_LAS bf16x8*)(lds + PG8_SA(b, h) + aoff + m * 2048 + k * 1024); } while (0)
; #define PG8_LDB(dst, b, h) do { _Pragma("unroll") for (int n = 0; n < 2; ++n) _Pragma("unroll") for (int k = 0; k < 2; ++k) dst[n][k] = *(const PG8_LAS bf16x8*)(lds + PG8_SB(b, h) + boff + n * 2048 + k * 1024); } while (0)
;     __host__ __device__ bool next(int i, Unit& u) const {
;         const long L = (long)i * G + c; if (L >= nwg) return false;
;         int wgid = (int)L; { const int q = nwg / NXCD, r = nwg % NXCD, xcd = wgid % NXCD, off = wgid / NXCD; wgid = (xcd < r ? xcd * (q + 1) : r * (q + 1) + (xcd - r) * q) + off; }
;         const int nig = WGM * nN, gid = wgid / nig, fm = gid * WGM, gsz = (nM - fm) < WGM ? (nM - fm) : WGM;
;         u.pm = fm + ((wgid % nig) % gsz); u.pn = (wgid % nig) / gsz; return true;
; template <class Epi, class Sched, bool ALIGN_EPI = false, bool SP2 = false, bool TA = true>
; __device__ __forceinline__ void gemm_phase(PG8_LAS unsigned char* lds, const Gemm g, const Sched& S, const Epi& E) {
;     ...
;         const bool has_next = S.next(ui + 1, nxt);
;         const char* nA = has_next ? (const char*)g.A + (size_t)nxt.pm * tstep : cA; const char* nB = has_next ? (const char*)g.Bt + (size_t)nxt.pn * tstep : cB;
; #pragma unroll 1
;         for (int t = 0; t < nt; t += 2) {
;             const bool last = (t == nt - 2);
;             const char* a1 = cA + (size_t)(t + 1) * kstep;
;             const char* a2 = last ? nA : cA + (size_t)(t + 2) * kstep; const char* b2 = last ? nB : cB + (size_t)(t + 2) * kstepB;
;             const char* a3 = a2 + kstep; const char* b3 = b2 + kstepB;
;             if (last && has_next) S.a_ready(nxt);
;             if constexpr (SP2) {
;             PG8_LDB(B0, 0, 0); PG8_LDB(B1, 0, 1); PG8_SCHED; PG8_LDA(At, 0, 0); PG8_STAGE(PG8_SA(1, 1), a1 + hstep, voffA);
;             PG8_WAIT_V(8); PG8_WAIT_L(0); PG8_BAR; PG8_MMA(0, 0, At, B0); PG8_MMA(0, 1, At, B1); PG8_BAR; PG8_SCHED;
.LBB0_1622:
	s_add_u32 s56, s56, 0x44000
	s_addc_u32 s57, s57, 0
	s_add_u32 s58, s58, 0x8000
	s_addc_u32 s59, s59, 0
	s_mov_b32 s74, -2
	ds_read_b128 v[136:139], v147
	ds_read_b128 v[152:155], v147 offset:1024
	ds_read_b128 v[156:159], v147 offset:2048
	ds_read_b128 v[160:163], v147 offset:3072
	ds_read_b128 v[164:167], v148
	ds_read_b128 v[168:171], v148 offset:1024
	ds_read_b128 v[172:175], v148 offset:2048
	ds_read_b128 v[176:179], v148 offset:3072
	s_add_u32 s75, s56, 0xfffc4000
	s_addc_u32 s76, s57, -1
	s_cmp_eq_u32 s74, 12
	s_cselect_b32 s77, s47, s76
	s_cselect_b32 s76, s55, s75
	s_cselect_b32 s79, s45, s59
	s_cselect_b32 s78, s73, s58
	v_lshl_add_u64 v[140:141], s[56:57], 0, v[128:129]
	s_add_i32 m0, s23, 0xc000
	ds_read_b128 v[180:183], v149
	ds_read_b128 v[184:187], v149 offset:1024
	ds_read_b128 v[188:191], v149 offset:2048
	ds_read_b128 v[192:195], v149 offset:3072
	ds_read_b128 v[196:199], v149 offset:4096
	ds_read_b128 v[200:203], v149 offset:5120
	ds_read_b128 v[204:207], v149 offset:6144
	ds_read_b128 v[210:213], v149 offset:7168
	global_load_lds_dwordx4 v[140:141], off
	v_lshl_add_u64 v[140:141], v[140:141], 0, s[6:7]
	s_add_i32 m0, s23, 0xe000
	s_nop 0
	global_load_lds_dwordx4 v[140:141], off
	s_add_i32 s72, s53, 1
	s_mul_i32 s4, s72, s67
	s_mul_hi_u32 s5, s72, s68
	s_add_i32 s5, s5, s4
	s_mul_i32 s4, s72, s68
	s_add_u32 s48, s4, s20
	s_addc_u32 s49, s5, s18
	v_cmp_gt_i64_e32 vcc, s[48:49], v[134:135]
	v_cmp_lt_i64_e64 s[4:5], s[48:49], v[132:133]
	s_cbranch_vccnz .LBB0_1624
	s_ashr_i32 s44, s48, 31
	s_lshr_b32 s44, s44, 29
	s_add_i32 s44, s48, s44
	s_ashr_i32 s45, s44, 3
	s_and_b32 s44, s44, -8
	s_sub_i32 s44, s48, s44
	s_cmp_lt_i32 s44, 0
	s_cselect_b32 s46, s69, 0x160
	s_mul_i32 s44, s44, s46
	s_add_i32 s44, s44, s45
	s_mul_hi_i32 s45, s44, 0x2e8ba2e9
	s_lshr_b32 s46, s45, 31
	s_ashr_i32 s45, s45, 5
	s_add_i32 s45, s45, s46
	s_lshl_b32 s46, s45, 3
	s_sub_i32 s47, 0x80, s46
	s_min_i32 s47, s47, 8
	s_abs_i32 s48, s47
	v_cvt_f32_u32_e32 v0, s48
	s_sub_i32 s50, 0, s48
	s_mulk_i32 s45, 0xb0
	s_sub_i32 s45, s44, s45
	v_rcp_iflag_f32_e32 v0, v0
	s_abs_i32 s44, s45
	s_xor_b32 s49, s45, s47
	s_ashr_i32 s49, s49, 31
	v_mul_f32_e32 v0, 0x4f7ffffe, v0
	v_cvt_u32_f32_e32 v0, v0
	s_nop 0
	v_readfirstlane_b32 s51, v0
	s_mul_i32 s50, s50, s51
	s_mul_hi_u32 s50, s51, s50
	s_add_i32 s51, s51, s50
	s_mul_hi_u32 s50, s44, s51
	s_mul_i32 s51, s50, s48
	s_sub_i32 s44, s44, s51
	s_add_i32 s55, s50, 1
	s_sub_i32 s51, s44, s48
	s_cmp_ge_u32 s44, s48
	s_cselect_b32 s50, s55, s50
	s_cselect_b32 s44, s51, s44
	s_add_i32 s51, s50, 1
	s_cmp_ge_u32 s44, s48
	s_cselect_b32 s44, s51, s50
	s_xor_b32 s44, s44, s49
	s_sub_i32 s44, s44, s49
	s_mul_i32 s47, s44, s47
	s_sub_i32 s45, s45, s47
	s_add_i32 s46, s46, s45
.LBB0_1624:
	s_ashr_i32 s47, s46, 31
	s_lshl_b64 s[48:49], s[46:47], 19
	s_add_u32 s48, s8, s48
	s_addc_u32 s49, s9, s49
	s_and_b64 s[50:51], s[4:5], exec
	s_cselect_b32 s47, s49, s57
	s_cselect_b32 s55, s48, s56
	s_ashr_i32 s45, s44, 31
	s_lshl_b64 s[50:51], s[44:45], 19
	s_add_u32 s50, s19, s50
	s_addc_u32 s51, s21, s51
	s_and_b64 s[98:99], s[4:5], exec
	s_cselect_b32 s45, s51, s59
	s_cselect_b32 s73, s50, s58
	s_waitcnt vmcnt(8)
	s_waitcnt lgkmcnt(0)
	s_barrier
	s_setprio 1
	s_waitcnt lgkmcnt(0)
	v_mfma_f32_16x16x32_bf16 v[124:127], v[136:139], v[180:183], 0
	v_mfma_f32_16x16x32_bf16 v[116:119], v[156:159], v[180:183], 0
	v_mfma_f32_16x16x32_bf16 v[108:111], v[136:139], v[188:191], 0
	v_mfma_f32_16x16x32_bf16 v[100:103], v[156:159], v[188:191], 0
	v_mfma_f32_16x16x32_bf16 v[92:95], v[136:139], v[196:199], 0
	v_mfma_f32_16x16x32_bf16 v[84:87], v[156:159], v[196:199], 0
	v_mfma_f32_16x16x32_bf16 v[76:79], v[136:139], v[204:207], 0
	v_mfma_f32_16x16x32_bf16 v[68:71], v[156:159], v[204:207], 0
	v_mfma_f32_16x16x32_bf16 v[124:127], v[152:155], v[184:187], v[124:127]
	v_mfma_f32_16x16x32_bf16 v[116:119], v[160:163], v[184:187], v[116:119]
	v_mfma_f32_16x16x32_bf16 v[108:111], v[152:155], v[192:195], v[108:111]
	v_mfma_f32_16x16x32_bf16 v[100:103], v[160:163], v[192:195], v[100:103]
	v_mfma_f32_16x16x32_bf16 v[92:95], v[152:155], v[200:203], v[92:95]
	v_mfma_f32_16x16x32_bf16 v[84:87], v[160:163], v[200:203], v[84:87]
	v_mfma_f32_16x16x32_bf16 v[76:79], v[152:155], v[210:213], v[76:79]
	v_mfma_f32_16x16x32_bf16 v[68:71], v[160:163], v[210:213], v[68:71]
	s_setprio 0
	s_setprio 1
	v_mfma_f32_16x16x32_bf16 v[120:123], v[164:167], v[180:183], 0
	v_mfma_f32_16x16x32_bf16 v[112:115], v[172:175], v[180:183], 0
	v_mfma_f32_16x16x32_bf16 v[104:107], v[164:167], v[188:191], 0
	v_mfma_f32_16x16x32_bf16 v[96:99], v[172:175], v[188:191], 0
	v_mfma_f32_16x16x32_bf16 v[88:91], v[164:167], v[196:199], 0
	v_mfma_f32_16x16x32_bf16 v[80:83], v[172:175], v[196:199], 0
	v_mfma_f32_16x16x32_bf16 v[72:75], v[164:167], v[204:207], 0
	v_mfma_f32_16x16x32_bf16 v[64:67], v[172:175], v[204:207], 0
	v_mfma_f32_16x16x32_bf16 v[120:123], v[168:171], v[184:187], v[120:123]
	v_mfma_f32_16x16x32_bf16 v[112:115], v[176:179], v[184:187], v[112:115]
	v_mfma_f32_16x16x32_bf16 v[104:107], v[168:171], v[192:195], v[104:107]
	v_mfma_f32_16x16x32_bf16 v[96:99], v[176:179], v[192:195], v[96:99]
	v_mfma_f32_16x16x32_bf16 v[88:91], v[168:171], v[200:203], v[88:91]
	v_mfma_f32_16x16x32_bf16 v[80:83], v[176:179], v[200:203], v[80:83]
	v_mfma_f32_16x16x32_bf16 v[72:75], v[168:171], v[210:213], v[72:75]
	v_mfma_f32_16x16x32_bf16 v[64:67], v[176:179], v[210:213], v[64:67]
	s_setprio 0
	s_barrier
; #define PG8_STAGE(bufoff, gbase, voff) do { _Pragma("unroll") for (int _i = 0; _i < 2; ++_i) \
;         __builtin_amdgcn_global_load_lds((const unsigned*)((const char*)(gbase) + (voff)[_i]), (PG8_LAS unsigned*)(lds + (bufoff) + ldsw + _i * 8192), 16, 0, 0); } while (0)
; #define PG8_LDA(dst, b, h) do { _Pragma("unroll") for (int m = 0; m < 4; ++m) _Pragma("unroll") for (int k = 0; k < 2; ++k) dst[m][k] = *(const PG8_LAS bf16x8*)(lds + PG8_SA(b, h) + aoff + m * 2048 + k * 1024); } while (0)
; #define PG8_LDB(dst, b, h) do { _Pragma("unroll") for (int n = 0; n < 2; ++n) _Pragma("unroll") for (int k = 0; k < 2; ++k) dst[n][k] = *(const PG8_LAS bf16x8*)(lds + PG8_SB(b, h) + boff + n * 2048 + k * 1024); } while (0)
; #define PG8_MMA(ai, bj, At, Bt) do { __builtin_amdgcn_s_setprio(1); _Pragma("unroll") for (int m = 0; m < 4; ++m) _Pragma("unroll") for (int n = 0; n < 2; ++n) _Pragma("unroll") for (int k = 0; k < 2; ++k) \
;         acc[ai][bj][m][n] = __builtin_amdgcn_mfma_f32_16x16x32_bf16(Bt[n][k], At[m][k], acc[ai][bj][m][n], 0, 0, 0); __builtin_amdgcn_s_setprio(0); } while (0)
; #define PG8_WAIT_V(n) asm volatile("s_waitcnt vmcnt(" #n ")" ::: "memory")
; #define PG8_WAIT_L(n) asm volatile("s_waitcnt lgkmcnt(" #n ")" ::: "memory")
; #define PG8_BAR __builtin_amdgcn_s_barrier()
; #define PG8_SCHED __builtin_amdgcn_sched_barrier(0)
; template <class Epi, class Sched, bool ALIGN_EPI = false, bool SP2 = false, bool TA = true>
; __device__ __forceinline__ void gemm_phase(PG8_LAS unsigned char* lds, const Gemm g, const Sched& S, const Epi& E) {
;     ...
;             PG8_LDA(At, 0, 1); PG8_STAGE(PG8_SB(0, 0), b2, voffB); PG8_STAGE(PG8_SB(0, 1), b2 + hstep, voffB); PG8_STAGE(PG8_SA(0, 0), a2, voffA);
;             PG8_WAIT_V(8); PG8_WAIT_L(0); PG8_BAR; PG8_MMA(1, 0, At, B0); PG8_MMA(1, 1, At, B1); PG8_BAR; PG8_SCHED;
;             PG8_LDB(B0, 1, 0); PG8_LDB(B1, 1, 1); PG8_SCHED; PG8_LDA(At, 1, 0); PG8_STAGE(PG8_SA(0, 1), a2 + hstep, voffA);
;             PG8_WAIT_V(8); PG8_WAIT_L(0); PG8_BAR; PG8_MMA(0, 0, At, B0); PG8_MMA(0, 1, At, B1); PG8_BAR; PG8_SCHED;
	s_add_i32 s75, s70, s22
	v_lshl_add_u64 v[140:141], s[78:79], 0, v[128:129]
	s_mov_b32 m0, s75
	ds_read_b128 v[180:183], v149 offset:16384
	ds_read_b128 v[184:187], v149 offset:17408
	ds_read_b128 v[188:191], v149 offset:18432
	ds_read_b128 v[192:195], v149 offset:19456
	ds_read_b128 v[196:199], v149 offset:20480
	ds_read_b128 v[200:203], v149 offset:21504
	ds_read_b128 v[204:207], v149 offset:22528
	ds_read_b128 v[210:213], v149 offset:23552
	global_load_lds_dwordx4 v[140:141], off
	v_lshl_add_u64 v[214:215], v[140:141], 0, s[6:7]
	s_add_i32 m0, s75, 0x2000
	s_add_i32 s75, s71, s22
	global_load_lds_dwordx4 v[214:215], off
	v_lshl_add_u64 v[214:215], v[140:141], 0, s[12:13]
	s_mov_b32 m0, s75
	s_nop 0
	global_load_lds_dwordx4 v[214:215], off
	v_lshl_add_u64 v[214:215], v[140:141], 0, s[14:15]
	s_add_i32 m0, s75, 0x2000
	s_nop 0
	global_load_lds_dwordx4 v[214:215], off
	v_lshl_add_u64 v[214:215], s[76:77], 0, v[128:129]
	s_mov_b32 m0, s23
	v_lshl_add_u64 v[216:217], v[214:215], 0, s[6:7]
	global_load_lds_dwordx4 v[214:215], off
	s_mov_b32 m0, s30
	s_nop 0
	global_load_lds_dwordx4 v[216:217], off
	s_waitcnt vmcnt(8)
	s_waitcnt lgkmcnt(0)
	s_barrier
	s_setprio 1
	s_waitcnt lgkmcnt(0)
	v_mfma_f32_16x16x32_bf16 v[60:63], v[136:139], v[180:183], 0
	v_mfma_f32_16x16x32_bf16 v[52:55], v[156:159], v[180:183], 0
	v_mfma_f32_16x16x32_bf16 v[44:47], v[136:139], v[188:191], 0
	v_mfma_f32_16x16x32_bf16 v[36:39], v[156:159], v[188:191], 0
	v_mfma_f32_16x16x32_bf16 v[28:31], v[136:139], v[196:199], 0
	v_mfma_f32_16x16x32_bf16 v[20:23], v[156:159], v[196:199], 0
	v_mfma_f32_16x16x32_bf16 v[12:15], v[136:139], v[204:207], 0
	v_mfma_f32_16x16x32_bf16 v[4:7], v[156:159], v[204:207], 0
	v_mfma_f32_16x16x32_bf16 v[60:63], v[152:155], v[184:187], v[60:63]
	v_mfma_f32_16x16x32_bf16 v[52:55], v[160:163], v[184:187], v[52:55]
	v_mfma_f32_16x16x32_bf16 v[44:47], v[152:155], v[192:195], v[44:47]
	v_mfma_f32_16x16x32_bf16 v[36:39], v[160:163], v[192:195], v[36:39]
	v_mfma_f32_16x16x32_bf16 v[28:31], v[152:155], v[200:203], v[28:31]
	v_mfma_f32_16x16x32_bf16 v[20:23], v[160:163], v[200:203], v[20:23]
	v_mfma_f32_16x16x32_bf16 v[12:15], v[152:155], v[210:213], v[12:15]
	v_mfma_f32_16x16x32_bf16 v[4:7], v[160:163], v[210:213], v[4:7]
	s_setprio 0
	s_setprio 1
	v_mfma_f32_16x16x32_bf16 v[56:59], v[164:167], v[180:183], 0
	v_mfma_f32_16x16x32_bf16 v[48:51], v[172:175], v[180:183], 0
	v_mfma_f32_16x16x32_bf16 v[40:43], v[164:167], v[188:191], 0
	v_mfma_f32_16x16x32_bf16 v[32:35], v[172:175], v[188:191], 0
	v_mfma_f32_16x16x32_bf16 v[24:27], v[164:167], v[196:199], 0
	v_mfma_f32_16x16x32_bf16 v[16:19], v[172:175], v[196:199], 0
	v_mfma_f32_16x16x32_bf16 v[8:11], v[164:167], v[204:207], 0
	v_mfma_f32_16x16x32_bf16 v[0:3], v[172:175], v[204:207], 0
	v_mfma_f32_16x16x32_bf16 v[56:59], v[168:171], v[184:187], v[56:59]
	v_mfma_f32_16x16x32_bf16 v[48:51], v[176:179], v[184:187], v[48:51]
	v_mfma_f32_16x16x32_bf16 v[40:43], v[168:171], v[192:195], v[40:43]
	v_mfma_f32_16x16x32_bf16 v[32:35], v[176:179], v[192:195], v[32:35]
	v_mfma_f32_16x16x32_bf16 v[24:27], v[168:171], v[200:203], v[24:27]
	v_mfma_f32_16x16x32_bf16 v[16:19], v[176:179], v[200:203], v[16:19]
	v_mfma_f32_16x16x32_bf16 v[8:11], v[168:171], v[210:213], v[8:11]
	v_mfma_f32_16x16x32_bf16 v[0:3], v[176:179], v[210:213], v[0:3]
	s_setprio 0
	s_barrier
	s_add_i32 s75, 0, 0x18000
	v_add_u32_e32 v130, s75, v144
	s_add_i32 s76, 0, 0x1c000
	ds_read_b128 v[136:139], v130
	ds_read_b128 v[152:155], v130 offset:1024
	ds_read_b128 v[156:159], v130 offset:2048
	ds_read_b128 v[160:163], v130 offset:3072
	v_add_u32_e32 v130, s76, v144
	ds_read_b128 v[164:167], v130
	ds_read_b128 v[168:171], v130 offset:1024
	ds_read_b128 v[172:175], v130 offset:2048
	ds_read_b128 v[176:179], v130 offset:3072
	s_mov_b32 m0, s31
	v_lshl_add_u64 v[216:217], v[214:215], 0, s[12:13]
	ds_read_b128 v[180:183], v149 offset:32768
	ds_read_b128 v[184:187], v149 offset:33792
	ds_read_b128 v[188:191], v149 offset:34816
	ds_read_b128 v[192:195], v149 offset:35840
	ds_read_b128 v[196:199], v149 offset:36864
	ds_read_b128 v[200:203], v149 offset:37888
	ds_read_b128 v[204:207], v149 offset:38912
	ds_read_b128 v[210:213], v149 offset:39936
	global_load_lds_dwordx4 v[216:217], off
	v_lshl_add_u64 v[216:217], v[214:215], 0, s[14:15]
	s_mov_b32 m0, s33
	s_nop 0
	global_load_lds_dwordx4 v[216:217], off
	s_waitcnt vmcnt(8)
	s_waitcnt lgkmcnt(0)
	s_barrier
; #define PG8_STAGE(bufoff, gbase, voff) do { _Pragma("unroll") for (int _i = 0; _i < 2; ++_i) \
;         __builtin_amdgcn_global_load_lds((const unsigned*)((const char*)(gbase) + (voff)[_i]), (PG8_LAS unsigned*)(lds + (bufoff) + ldsw + _i * 8192), 16, 0, 0); } while (0)
; #define PG8_LDA(dst, b, h) do { _Pragma("unroll") for (int m = 0; m < 4; ++m) _Pragma("unroll") for (int k = 0; k < 2; ++k) dst[m][k] = *(const PG8_LAS bf16x8*)(lds + PG8_SA(b, h) + aoff + m * 2048 + k * 1024); } while (0)
; #define PG8_MMA(ai, bj, At, Bt) do { __builtin_amdgcn_s_setprio(1); _Pragma("unroll") for (int m = 0; m < 4; ++m) _Pragma("unroll") for (int n = 0; n < 2; ++n) _Pragma("unroll") for (int k = 0; k < 2; ++k) \
;         acc[ai][bj][m][n] = __builtin_amdgcn_mfma_f32_16x16x32_bf16(Bt[n][k], At[m][k], acc[ai][bj][m][n], 0, 0, 0); __builtin_amdgcn_s_setprio(0); } while (0)
; #define PG8_WAIT_V(n) asm volatile("s_waitcnt vmcnt(" #n ")" ::: "memory")
; #define PG8_WAIT_L(n) asm volatile("s_waitcnt lgkmcnt(" #n ")" ::: "memory")
; #define PG8_BAR __builtin_amdgcn_s_barrier()
; #define PG8_SCHED __builtin_amdgcn_sched_barrier(0)
; template <class Epi, class Sched, bool ALIGN_EPI = false, bool SP2 = false, bool TA = true>
; __device__ __forceinline__ void gemm_phase(PG8_LAS unsigned char* lds, const Gemm g, const Sched& S, const Epi& E) {
;     ...
;         for (int t = 0; t < nt; t += 2) {
;     ...
;             PG8_WAIT_V(8); PG8_WAIT_L(0); PG8_BAR; PG8_MMA(0, 0, At, B0); PG8_MMA(0, 1, At, B1); PG8_BAR; PG8_SCHED;
;             PG8_LDA(At, 1, 1); PG8_STAGE(PG8_SB(1, 0), b3, voffB); PG8_STAGE(PG8_SB(1, 1), b3 + hstep, voffB); PG8_STAGE(PG8_SA(1, 0), a3, voffA);
;             PG8_WAIT_V(8); PG8_WAIT_L(0); PG8_BAR; PG8_MMA(1, 0, At, B0); PG8_MMA(1, 1, At, B1); PG8_BAR; PG8_SCHED;
	s_setprio 1
	s_waitcnt lgkmcnt(0)
	v_mfma_f32_16x16x32_bf16 v[124:127], v[136:139], v[180:183], v[124:127]
	v_mfma_f32_16x16x32_bf16 v[116:119], v[156:159], v[180:183], v[116:119]
	v_mfma_f32_16x16x32_bf16 v[108:111], v[136:139], v[188:191], v[108:111]
	v_mfma_f32_16x16x32_bf16 v[100:103], v[156:159], v[188:191], v[100:103]
	v_mfma_f32_16x16x32_bf16 v[92:95], v[136:139], v[196:199], v[92:95]
	v_mfma_f32_16x16x32_bf16 v[84:87], v[156:159], v[196:199], v[84:87]
	v_mfma_f32_16x16x32_bf16 v[76:79], v[136:139], v[204:207], v[76:79]
	v_mfma_f32_16x16x32_bf16 v[68:71], v[156:159], v[204:207], v[68:71]
	v_mfma_f32_16x16x32_bf16 v[124:127], v[152:155], v[184:187], v[124:127]
	v_mfma_f32_16x16x32_bf16 v[116:119], v[160:163], v[184:187], v[116:119]
	v_mfma_f32_16x16x32_bf16 v[108:111], v[152:155], v[192:195], v[108:111]
	v_mfma_f32_16x16x32_bf16 v[100:103], v[160:163], v[192:195], v[100:103]
	v_mfma_f32_16x16x32_bf16 v[92:95], v[152:155], v[200:203], v[92:95]
	v_mfma_f32_16x16x32_bf16 v[84:87], v[160:163], v[200:203], v[84:87]
	v_mfma_f32_16x16x32_bf16 v[76:79], v[152:155], v[210:213], v[76:79]
	v_mfma_f32_16x16x32_bf16 v[68:71], v[160:163], v[210:213], v[68:71]
	s_setprio 0
	s_setprio 1
	v_mfma_f32_16x16x32_bf16 v[120:123], v[164:167], v[180:183], v[120:123]
	v_mfma_f32_16x16x32_bf16 v[112:115], v[172:175], v[180:183], v[112:115]
	v_mfma_f32_16x16x32_bf16 v[104:107], v[164:167], v[188:191], v[104:107]
	v_mfma_f32_16x16x32_bf16 v[96:99], v[172:175], v[188:191], v[96:99]
	v_mfma_f32_16x16x32_bf16 v[88:91], v[164:167], v[196:199], v[88:91]
	v_mfma_f32_16x16x32_bf16 v[80:83], v[172:175], v[196:199], v[80:83]
	v_mfma_f32_16x16x32_bf16 v[72:75], v[164:167], v[204:207], v[72:75]
	v_mfma_f32_16x16x32_bf16 v[64:67], v[172:175], v[204:207], v[64:67]
	v_mfma_f32_16x16x32_bf16 v[120:123], v[168:171], v[184:187], v[120:123]
	v_mfma_f32_16x16x32_bf16 v[112:115], v[176:179], v[184:187], v[112:115]
	v_mfma_f32_16x16x32_bf16 v[104:107], v[168:171], v[192:195], v[104:107]
	v_mfma_f32_16x16x32_bf16 v[96:99], v[176:179], v[192:195], v[96:99]
	v_mfma_f32_16x16x32_bf16 v[88:91], v[168:171], v[200:203], v[88:91]
	v_mfma_f32_16x16x32_bf16 v[80:83], v[176:179], v[200:203], v[80:83]
	v_mfma_f32_16x16x32_bf16 v[72:75], v[168:171], v[210:213], v[72:75]
	v_mfma_f32_16x16x32_bf16 v[64:67], v[176:179], v[210:213], v[64:67]
	s_setprio 0
	s_barrier
	s_add_i32 s75, s75, s22
	v_lshl_add_u64 v[216:217], v[140:141], 0, s[34:35]
	s_mov_b32 m0, s75
	ds_read_b128 v[180:183], v149 offset:49152
	ds_read_b128 v[184:187], v149 offset:50176
	ds_read_b128 v[188:191], v149 offset:51200
	ds_read_b128 v[192:195], v149 offset:52224
	ds_read_b128 v[196:199], v149 offset:53248
	ds_read_b128 v[200:203], v149 offset:54272
	ds_read_b128 v[204:207], v149 offset:55296
	ds_read_b128 v[210:213], v149 offset:56320
	global_load_lds_dwordx4 v[216:217], off
	v_lshl_add_u64 v[216:217], v[140:141], 0, s[36:37]
	s_add_i32 m0, s75, 0x2000
	s_add_i32 s75, s76, s22
	global_load_lds_dwordx4 v[216:217], off
	v_lshl_add_u64 v[216:217], v[140:141], 0, s[38:39]
	s_mov_b32 m0, s75
	v_lshl_add_u64 v[140:141], v[140:141], 0, s[40:41]
	global_load_lds_dwordx4 v[216:217], off
	s_add_i32 m0, s75, 0x2000
	s_nop 0
	global_load_lds_dwordx4 v[140:141], off
	v_lshl_add_u64 v[140:141], v[214:215], 0, s[34:35]
	s_mov_b32 m0, s60
	s_nop 0
	global_load_lds_dwordx4 v[140:141], off
	v_lshl_add_u64 v[140:141], v[214:215], 0, s[36:37]
	s_mov_b32 m0, s61
	s_nop 0
	global_load_lds_dwordx4 v[140:141], off
	s_waitcnt vmcnt(8)
	s_waitcnt lgkmcnt(0)
	s_barrier
	s_setprio 1
	s_waitcnt lgkmcnt(0)
	v_mfma_f32_16x16x32_bf16 v[60:63], v[136:139], v[180:183], v[60:63]
	v_mfma_f32_16x16x32_bf16 v[52:55], v[156:159], v[180:183], v[52:55]
	v_mfma_f32_16x16x32_bf16 v[44:47], v[136:139], v[188:191], v[44:47]
	v_mfma_f32_16x16x32_bf16 v[36:39], v[156:159], v[188:191], v[36:39]
	v_mfma_f32_16x16x32_bf16 v[28:31], v[136:139], v[196:199], v[28:31]
	v_mfma_f32_16x16x32_bf16 v[20:23], v[156:159], v[196:199], v[20:23]
	v_mfma_f32_16x16x32_bf16 v[12:15], v[136:139], v[204:207], v[12:15]
	v_mfma_f32_16x16x32_bf16 v[4:7], v[156:159], v[204:207], v[4:7]
	v_mfma_f32_16x16x32_bf16 v[60:63], v[152:155], v[184:187], v[60:63]
	v_mfma_f32_16x16x32_bf16 v[52:55], v[160:163], v[184:187], v[52:55]
	v_mfma_f32_16x16x32_bf16 v[44:47], v[152:155], v[192:195], v[44:47]
	v_mfma_f32_16x16x32_bf16 v[36:39], v[160:163], v[192:195], v[36:39]
	v_mfma_f32_16x16x32_bf16 v[28:31], v[152:155], v[200:203], v[28:31]
	v_mfma_f32_16x16x32_bf16 v[20:23], v[160:163], v[200:203], v[20:23]
	v_mfma_f32_16x16x32_bf16 v[12:15], v[152:155], v[210:213], v[12:15]
	v_mfma_f32_16x16x32_bf16 v[4:7], v[160:163], v[210:213], v[4:7]
	s_setprio 0
	s_setprio 1
	v_mfma_f32_16x16x32_bf16 v[56:59], v[164:167], v[180:183], v[56:59]
	v_mfma_f32_16x16x32_bf16 v[48:51], v[172:175], v[180:183], v[48:51]
	v_mfma_f32_16x16x32_bf16 v[40:43], v[164:167], v[188:191], v[40:43]
	v_mfma_f32_16x16x32_bf16 v[32:35], v[172:175], v[188:191], v[32:35]
	v_mfma_f32_16x16x32_bf16 v[24:27], v[164:167], v[196:199], v[24:27]
	v_mfma_f32_16x16x32_bf16 v[16:19], v[172:175], v[196:199], v[16:19]
	v_mfma_f32_16x16x32_bf16 v[8:11], v[164:167], v[204:207], v[8:11]
	v_mfma_f32_16x16x32_bf16 v[0:3], v[172:175], v[204:207], v[0:3]
	v_mfma_f32_16x16x32_bf16 v[56:59], v[168:171], v[184:187], v[56:59]
	v_mfma_f32_16x16x32_bf16 v[48:51], v[176:179], v[184:187], v[48:51]
	v_mfma_f32_16x16x32_bf16 v[40:43], v[168:171], v[192:195], v[40:43]
	v_mfma_f32_16x16x32_bf16 v[32:35], v[176:179], v[192:195], v[32:35]
	v_mfma_f32_16x16x32_bf16 v[24:27], v[168:171], v[200:203], v[24:27]
	v_mfma_f32_16x16x32_bf16 v[16:19], v[176:179], v[200:203], v[16:19]
	v_mfma_f32_16x16x32_bf16 v[8:11], v[168:171], v[210:213], v[8:11]
	v_mfma_f32_16x16x32_bf16 v[0:3], v[176:179], v[210:213], v[0:3]
	s_setprio 0
	s_barrier
	s_add_i32 s74, s74, 2
	s_add_u32 s56, s56, 0x8000
	s_addc_u32 s57, s57, 0
	s_add_u32 s58, s58, 0x8000
	s_addc_u32 s59, s59, 0
	s_cmp_gt_u32 s74, 13
